# gate math: sqrt(1-a^2)/(1+e_i) evaluated as t*rsq(t*(1+e_i)^2) (one transcendental fewer per element, guarded against t=0), both passes
# baseline (speedup 1.0000x reference)
; #define LAS __attribute__((address_space(3)))
; template <int dir>
; __device__ __forceinline__ void lru_pass(LAS unsigned char* lds, const Params& P, int b, int h, int q, bool dry) {
;     ...
;             const int sbase = 32 * wid + 16 * g;
;             { const int sl = 32 * wid + s_i; const int tlA = dir == 0 ? sl : 255 - sl;
;               const LAS unsigned char* ap = XC + tlA * XC_PITCH + 16 * g;
;               const LAS unsigned char* wrp = WB + nl * XC_PITCH + 16 * g; const LAS unsigned char* wip = wrp + 32 * XC_PITCH;
; #pragma unroll
;               for (int ks = 0; ks < 8; ++ks) { const bf16x8 A = *(const LAS bf16x8*)(ap + 32 * ks);
;                   const bf16x8 Br = *(const LAS bf16x8*)(wrp + 32 * ks), Bi = *(const LAS bf16x8*)(wip + 32 * ks);
;                   zr = __builtin_amdgcn_mfma_f32_32x32x16_bf16(A, Br, zr, 0, 0, 0); zi = __builtin_amdgcn_mfma_f32_32x32x16_bf16(A, Bi, zi, 0, 0, 0); } }
;             unsigned xcb[16], pk[16];
; #pragma unroll
;             for (int v = 0; v < 16; ++v) { const int s = sbase + v; const int tl = dir == 0 ? s : 255 - s; xcb[v] = *(const LAS bf16_t*)(XC + tl * XC_PITCH + chl * 2);
;                 if (dir == 0) pk[v] = *(const LAS bf16_t*)(TIN + tl * IO_NP + nl * 2); else pk[v] = *(const LAS unsigned*)(TIN + tl * IO_WP + nl * 4); }
;             float Pp = 1.f, E = 0.f;
; #pragma unroll
;             for (int v = 0; v < 16; ++v) {
;                 const float xcv = __uint_as_float(xcb[v] << 16);
;                 const float r = __builtin_amdgcn_rcpf(1.0f + __builtin_amdgcn_exp2f(zr[v]));
;                 const float ig = __builtin_amdgcn_rcpf(1.0f + __builtin_amdgcn_exp2f(zi[v]));
;                 const float a = __builtin_amdgcn_exp2f(cl * r);
;                 const float sq = __builtin_amdgcn_sqrtf(fmaf(-a, a, 1.0f));
;                 const float u = sq * ig * xcv;
;                 E = fmaf(a, E, u); Pp *= a; zr[v] = E; zi[v] = Pp; }
.Llruf_wres:
	ds_read_b128 v[120:123], v160
	ds_read_b128 v[124:127], v160 offset:32
	ds_read_b128 v[168:171], v160 offset:64
	ds_read_b128 v[172:175], v160 offset:96
	ds_read_b128 v[176:179], v160 offset:128
	ds_read_b128 v[180:183], v160 offset:160
	ds_read_b128 v[184:187], v160 offset:192
	ds_read_b128 v[188:191], v160 offset:224
	ds_read_b128 v[236:239], v161 offset:8704
	ds_read_b128 v[240:243], v161 offset:8736
	ds_read_b128 v[244:247], v161 offset:8768
	ds_read_b128 v[248:251], v161 offset:8800
	s_waitcnt lgkmcnt(11)
	v_mfma_f32_32x32x16_bf16 v[32:47], v[120:123], v[204:207], v[0:15]
	s_waitcnt lgkmcnt(10)
	v_mfma_f32_32x32x16_bf16 v[32:47], v[124:127], v[208:211], v[32:47]
	s_waitcnt lgkmcnt(9)
	v_mfma_f32_32x32x16_bf16 v[32:47], v[168:171], v[212:215], v[32:47]
	s_waitcnt lgkmcnt(8)
	v_mfma_f32_32x32x16_bf16 v[32:47], v[172:175], v[216:219], v[32:47]
	s_waitcnt lgkmcnt(7)
	v_mfma_f32_32x32x16_bf16 v[32:47], v[176:179], v[220:223], v[32:47]
	s_waitcnt lgkmcnt(6)
	v_mfma_f32_32x32x16_bf16 v[32:47], v[180:183], v[224:227], v[32:47]
	s_waitcnt lgkmcnt(5)
	v_mfma_f32_32x32x16_bf16 v[32:47], v[184:187], v[228:231], v[32:47]
	s_waitcnt lgkmcnt(4)
	v_mfma_f32_32x32x16_bf16 v[32:47], v[188:191], v[232:235], v[32:47]
	s_waitcnt lgkmcnt(3)
	v_mfma_f32_32x32x16_bf16 v[48:63], v[120:123], v[236:239], v[16:31]
	ds_read_b128 v[236:239], v161 offset:8832
	s_nop 9
	v_exp_f32_e32 v32, v32
	v_exp_f32_e32 v33, v33
	v_exp_f32_e32 v34, v34
	v_exp_f32_e32 v35, v35
	v_exp_f32_e32 v36, v36
	v_exp_f32_e32 v37, v37
	v_exp_f32_e32 v38, v38
	v_exp_f32_e32 v39, v39
	s_waitcnt lgkmcnt(3)
	v_mfma_f32_32x32x16_bf16 v[48:63], v[124:127], v[240:243], v[48:63]
	ds_read_b128 v[240:243], v161 offset:8864
	v_exp_f32_e32 v40, v40
	v_exp_f32_e32 v41, v41
	v_exp_f32_e32 v42, v42
	v_exp_f32_e32 v43, v43
	v_exp_f32_e32 v44, v44
	v_exp_f32_e32 v45, v45
	v_exp_f32_e32 v46, v46
	v_exp_f32_e32 v47, v47
	s_waitcnt lgkmcnt(3)
	v_mfma_f32_32x32x16_bf16 v[48:63], v[168:171], v[244:247], v[48:63]
	ds_read_b128 v[244:247], v161 offset:8896
	v_fma_f32 v32, v32, v138, v138
	v_fma_f32 v33, v33, v138, v138
	v_fma_f32 v34, v34, v138, v138
	v_fma_f32 v35, v35, v138, v138
	v_fma_f32 v36, v36, v138, v138
	v_fma_f32 v37, v37, v138, v138
	v_fma_f32 v38, v38, v138, v138
	v_fma_f32 v39, v39, v138, v138
	s_waitcnt lgkmcnt(3)
	v_mfma_f32_32x32x16_bf16 v[48:63], v[172:175], v[248:251], v[48:63]
	ds_read_b128 v[248:251], v161 offset:8928
	v_fma_f32 v40, v40, v138, v138
	v_fma_f32 v41, v41, v138, v138
	v_fma_f32 v42, v42, v138, v138
	v_fma_f32 v43, v43, v138, v138
	v_fma_f32 v44, v44, v138, v138
	v_fma_f32 v45, v45, v138, v138
	v_fma_f32 v46, v46, v138, v138
	v_fma_f32 v47, v47, v138, v138
	s_waitcnt lgkmcnt(3)
	v_mfma_f32_32x32x16_bf16 v[48:63], v[176:179], v[236:239], v[48:63]
	v_rcp_f32_e32 v32, v32
	v_rcp_f32_e32 v33, v33
	v_rcp_f32_e32 v34, v34
	v_rcp_f32_e32 v35, v35
	v_rcp_f32_e32 v36, v36
	v_rcp_f32_e32 v37, v37
	v_rcp_f32_e32 v38, v38
	v_rcp_f32_e32 v39, v39
	s_waitcnt lgkmcnt(2)
	v_mfma_f32_32x32x16_bf16 v[48:63], v[180:183], v[240:243], v[48:63]
	v_rcp_f32_e32 v40, v40
	v_rcp_f32_e32 v41, v41
	v_rcp_f32_e32 v42, v42
	v_rcp_f32_e32 v43, v43
	v_rcp_f32_e32 v44, v44
	v_rcp_f32_e32 v45, v45
	v_rcp_f32_e32 v46, v46
	v_rcp_f32_e32 v47, v47
	s_waitcnt lgkmcnt(1)
	v_mfma_f32_32x32x16_bf16 v[48:63], v[184:187], v[244:247], v[48:63]
	v_exp_f32_e32 v32, v32
	v_exp_f32_e32 v33, v33
	v_exp_f32_e32 v34, v34
	v_exp_f32_e32 v35, v35
	v_exp_f32_e32 v36, v36
	v_exp_f32_e32 v37, v37
	v_exp_f32_e32 v38, v38
	v_exp_f32_e32 v39, v39
	s_waitcnt lgkmcnt(0)
	v_mfma_f32_32x32x16_bf16 v[48:63], v[188:191], v[248:251], v[48:63]
	v_exp_f32_e32 v40, v40
	v_exp_f32_e32 v41, v41
	v_exp_f32_e32 v42, v42
	v_exp_f32_e32 v43, v43
	v_exp_f32_e32 v44, v44
	v_exp_f32_e32 v45, v45
	v_exp_f32_e32 v46, v46
	v_exp_f32_e32 v47, v47
	ds_read_u16 v152, v162
	ds_read_u16 v154, v162 offset:272
	ds_read_u16 v155, v162 offset:544
	ds_read_u16 v157, v162 offset:816
	ds_read_u16 v196, v162 offset:1088
	ds_read_u16 v197, v162 offset:1360
	ds_read_u16 v177, v162 offset:1632
	ds_read_u16 v178, v162 offset:1904
	ds_read_u16 v179, v162 offset:2176
	ds_read_u16 v180, v162 offset:2448
	ds_read_u16 v181, v162 offset:2720
	ds_read_u16 v182, v162 offset:2992
	ds_read_u16 v183, v162 offset:3264
	ds_read_u16 v184, v162 offset:3536
	ds_read_u16 v185, v162 offset:3808
	ds_read_u16 v187, v162 offset:4080
	v_exp_f32_e32 v48, v48
	v_exp_f32_e32 v49, v49
	v_exp_f32_e32 v50, v50
	v_exp_f32_e32 v51, v51
	v_exp_f32_e32 v52, v52
	v_exp_f32_e32 v53, v53
	v_exp_f32_e32 v54, v54
	v_exp_f32_e32 v55, v55
	v_exp_f32_e32 v56, v56
	v_exp_f32_e32 v57, v57
	v_exp_f32_e32 v58, v58
	v_exp_f32_e32 v59, v59
	v_exp_f32_e32 v60, v60
	v_exp_f32_e32 v61, v61
	v_exp_f32_e32 v62, v62
	v_exp_f32_e32 v63, v63
	v_add_f32_e32 v48, 1.0, v48
	v_add_f32_e32 v49, 1.0, v49
	v_add_f32_e32 v50, 1.0, v50
	v_add_f32_e32 v51, 1.0, v51
	v_add_f32_e32 v52, 1.0, v52
	v_add_f32_e32 v53, 1.0, v53
	v_add_f32_e32 v54, 1.0, v54
	v_add_f32_e32 v55, 1.0, v55
	v_add_f32_e32 v56, 1.0, v56
	v_add_f32_e32 v57, 1.0, v57
	v_add_f32_e32 v58, 1.0, v58
	v_add_f32_e32 v59, 1.0, v59
	v_add_f32_e32 v60, 1.0, v60
	v_add_f32_e32 v61, 1.0, v61
	v_add_f32_e32 v62, 1.0, v62
	v_add_f32_e32 v63, 1.0, v63
	s_waitcnt lgkmcnt(0)
; template <int dir>
; __device__ __forceinline__ void lru_pass(LAS unsigned char* lds, const Params& P, int b, int h, int q, bool dry) {
;     ...
;             for (int v = 0; v < 16; ++v) {
;                 const float xcv = __uint_as_float(xcb[v] << 16);
;                 const float r = __builtin_amdgcn_rcpf(1.0f + __builtin_amdgcn_exp2f(zr[v]));
;                 const float ig = __builtin_amdgcn_rcpf(1.0f + __builtin_amdgcn_exp2f(zi[v]));
;                 const float a = __builtin_amdgcn_exp2f(cl * r);
;                 const float sq = __builtin_amdgcn_sqrtf(fmaf(-a, a, 1.0f));
;                 const float u = sq * ig * xcv;
;                 E = fmaf(a, E, u); Pp *= a; zr[v] = E; zi[v] = Pp; }
;             const float Po = __shfl_xor(Pp, 32), Eo = __shfl_xor(E, 32);
;             const float P0 = g ? Po : Pp, E0 = g ? Eo : E, P1 = g ? Pp : Po, E1 = g ? E : Eo;
;             if (g == 0) { AGG[(wid * 2 + 0) * 32 + nl] = P0 * P1; AGG[(wid * 2 + 1) * 32 + nl] = fmaf(P1, E0, E1); }
	v_fma_f32 v120, -v32, v32, 1.0
	v_fma_f32 v121, -v33, v33, 1.0
	v_fma_f32 v122, -v34, v34, 1.0
	v_fma_f32 v123, -v35, v35, 1.0
	v_mul_f32_e32 v48, v48, v48
	v_mul_f32_e32 v49, v49, v49
	v_mul_f32_e32 v50, v50, v50
	v_mul_f32_e32 v51, v51, v51
	v_mul_f32_e32 v48, v48, v120
	v_mul_f32_e32 v49, v49, v121
	v_mul_f32_e32 v50, v50, v122
	v_mul_f32_e32 v51, v51, v123
	v_max_f32_e32 v48, 0x0da24260, v48
	v_max_f32_e32 v49, 0x0da24260, v49
	v_max_f32_e32 v50, 0x0da24260, v50
	v_max_f32_e32 v51, 0x0da24260, v51
	v_rsq_f32_e32 v48, v48
	v_rsq_f32_e32 v49, v49
	v_rsq_f32_e32 v50, v50
	v_rsq_f32_e32 v51, v51
	v_lshlrev_b32_e32 v152, 16, v152
	v_lshlrev_b32_e32 v154, 16, v154
	v_lshlrev_b32_e32 v155, 16, v155
	v_lshlrev_b32_e32 v157, 16, v157
	v_mul_f32_e32 v120, v120, v48
	v_mul_f32_e32 v121, v121, v49
	v_mul_f32_e32 v122, v122, v50
	v_mul_f32_e32 v123, v123, v51
	v_mul_f32_e32 v49, v120, v152
	v_mul_f32_e32 v172, v121, v154
	v_mul_f32_e32 v173, v122, v155
	v_mul_f32_e32 v174, v123, v157
	v_fma_f32 v120, -v36, v36, 1.0
	v_fma_f32 v121, -v37, v37, 1.0
	v_fma_f32 v122, -v38, v38, 1.0
	v_fma_f32 v123, -v39, v39, 1.0
	v_mul_f32_e32 v52, v52, v52
	v_mul_f32_e32 v53, v53, v53
	v_mul_f32_e32 v54, v54, v54
	v_mul_f32_e32 v55, v55, v55
	v_mul_f32_e32 v52, v52, v120
	v_mul_f32_e32 v53, v53, v121
	v_mul_f32_e32 v54, v54, v122
	v_mul_f32_e32 v55, v55, v123
	v_max_f32_e32 v52, 0x0da24260, v52
	v_max_f32_e32 v53, 0x0da24260, v53
	v_max_f32_e32 v54, 0x0da24260, v54
	v_max_f32_e32 v55, 0x0da24260, v55
	v_rsq_f32_e32 v52, v52
	v_rsq_f32_e32 v53, v53
	v_rsq_f32_e32 v54, v54
	v_rsq_f32_e32 v55, v55
	v_lshlrev_b32_e32 v196, 16, v196
	v_lshlrev_b32_e32 v197, 16, v197
	v_lshlrev_b32_e32 v177, 16, v177
	v_lshlrev_b32_e32 v178, 16, v178
	v_mul_f32_e32 v120, v120, v52
	v_mul_f32_e32 v121, v121, v53
	v_mul_f32_e32 v122, v122, v54
	v_mul_f32_e32 v123, v123, v55
	v_mul_f32_e32 v175, v120, v196
	v_mul_f32_e32 v176, v121, v197
	v_mul_f32_e32 v177, v122, v177
	v_mul_f32_e32 v178, v123, v178
	v_fma_f32 v120, -v40, v40, 1.0
	v_fma_f32 v121, -v41, v41, 1.0
	v_fma_f32 v122, -v42, v42, 1.0
	v_fma_f32 v123, -v43, v43, 1.0
	v_mul_f32_e32 v56, v56, v56
	v_mul_f32_e32 v57, v57, v57
	v_mul_f32_e32 v58, v58, v58
	v_mul_f32_e32 v59, v59, v59
	v_mul_f32_e32 v56, v56, v120
	v_mul_f32_e32 v57, v57, v121
	v_mul_f32_e32 v58, v58, v122
	v_mul_f32_e32 v59, v59, v123
	v_max_f32_e32 v56, 0x0da24260, v56
	v_max_f32_e32 v57, 0x0da24260, v57
	v_max_f32_e32 v58, 0x0da24260, v58
	v_max_f32_e32 v59, 0x0da24260, v59
	v_rsq_f32_e32 v56, v56
	v_rsq_f32_e32 v57, v57
	v_rsq_f32_e32 v58, v58
	v_rsq_f32_e32 v59, v59
	v_lshlrev_b32_e32 v179, 16, v179
	v_lshlrev_b32_e32 v180, 16, v180
	v_lshlrev_b32_e32 v181, 16, v181
	v_lshlrev_b32_e32 v182, 16, v182
	v_mul_f32_e32 v120, v120, v56
	v_mul_f32_e32 v121, v121, v57
	v_mul_f32_e32 v122, v122, v58
	v_mul_f32_e32 v123, v123, v59
	v_mul_f32_e32 v179, v120, v179
	v_mul_f32_e32 v180, v121, v180
	v_mul_f32_e32 v181, v122, v181
	v_mul_f32_e32 v182, v123, v182
	v_fma_f32 v120, -v44, v44, 1.0
	v_fma_f32 v121, -v45, v45, 1.0
	v_fma_f32 v122, -v46, v46, 1.0
	v_fma_f32 v123, -v47, v47, 1.0
	v_mul_f32_e32 v60, v60, v60
	v_mul_f32_e32 v61, v61, v61
	v_mul_f32_e32 v62, v62, v62
	v_mul_f32_e32 v63, v63, v63
	v_mul_f32_e32 v60, v60, v120
	v_mul_f32_e32 v61, v61, v121
	v_mul_f32_e32 v62, v62, v122
	v_mul_f32_e32 v63, v63, v123
	v_max_f32_e32 v60, 0x0da24260, v60
	v_max_f32_e32 v61, 0x0da24260, v61
	v_max_f32_e32 v62, 0x0da24260, v62
	v_max_f32_e32 v63, 0x0da24260, v63
	v_rsq_f32_e32 v60, v60
	v_rsq_f32_e32 v61, v61
	v_rsq_f32_e32 v62, v62
	v_rsq_f32_e32 v63, v63
	v_lshlrev_b32_e32 v183, 16, v183
	v_lshlrev_b32_e32 v184, 16, v184
	v_lshlrev_b32_e32 v185, 16, v185
	v_lshlrev_b32_e32 v187, 16, v187
	v_mul_f32_e32 v120, v120, v60
	v_mul_f32_e32 v121, v121, v61
	v_mul_f32_e32 v122, v122, v62
	v_mul_f32_e32 v123, v123, v63
	v_mul_f32_e32 v183, v120, v183
	v_mul_f32_e32 v184, v121, v184
	v_mul_f32_e32 v63, v122, v185
	v_mul_f32_e32 v185, v123, v187
	v_mov_b32_e32 v171, v32
	v_fmac_f32_e32 v49, 0, v32
	v_fmac_f32_e32 v172, v33, v49
	v_mul_f32_e32 v50, v171, v33
	v_fmac_f32_e32 v173, v34, v172
	v_mul_f32_e32 v51, v50, v34
	v_fmac_f32_e32 v174, v35, v173
	v_mul_f32_e32 v52, v51, v35
	v_fmac_f32_e32 v175, v36, v174
	v_mul_f32_e32 v53, v52, v36
	v_fmac_f32_e32 v176, v37, v175
	v_mul_f32_e32 v54, v53, v37
	v_fmac_f32_e32 v177, v38, v176
	v_mul_f32_e32 v55, v54, v38
	v_fmac_f32_e32 v178, v39, v177
	v_mul_f32_e32 v56, v55, v39
	v_fmac_f32_e32 v179, v40, v178
	v_mul_f32_e32 v57, v56, v40
	v_fmac_f32_e32 v180, v41, v179
	v_mul_f32_e32 v58, v57, v41
	v_fmac_f32_e32 v181, v42, v180
	v_mul_f32_e32 v59, v58, v42
	v_fmac_f32_e32 v182, v43, v181
	v_mul_f32_e32 v60, v59, v43
	v_fmac_f32_e32 v183, v44, v182
	v_mul_f32_e32 v61, v60, v44
	v_fmac_f32_e32 v184, v45, v183
	v_mul_f32_e32 v62, v61, v45
	v_fmac_f32_e32 v63, v46, v184
	v_mul_f32_e32 v186, v62, v46
	v_fmac_f32_e32 v185, v47, v63
	v_mul_f32_e32 v187, v186, v47
	v_mov_b32_e32 v188, v187
	v_mov_b32_e32 v252, v187
	v_mov_b32_e32 v189, v185
	v_mov_b32_e32 v253, v185
	s_nop 1
	v_permlane32_swap_b32 v188, v252
	v_permlane32_swap_b32 v189, v253
	s_and_saveexec_b64 s[18:19], vcc
	s_cbranch_execz .LBB0_299
	v_fma_f32 v32, v252, v189, v253
	v_mul_f32_e32 v33, v188, v252
	v_add_u32_e32 v35, s98, v147
	ds_write2_b32 v35, v33, v32 offset1:32

; #define LAS __attribute__((address_space(3)))
; template <int dir>
; __device__ __forceinline__ void lru_pass(LAS unsigned char* lds, const Params& P, int b, int h, int q, bool dry) {
;     ...
;             const int sbase = 32 * wid + 16 * g;
;             { const int sl = 32 * wid + s_i; const int tlA = dir == 0 ? sl : 255 - sl;
;               const LAS unsigned char* ap = XC + tlA * XC_PITCH + 16 * g;
;               const LAS unsigned char* wrp = WB + nl * XC_PITCH + 16 * g; const LAS unsigned char* wip = wrp + 32 * XC_PITCH;
; #pragma unroll
;               for (int ks = 0; ks < 8; ++ks) { const bf16x8 A = *(const LAS bf16x8*)(ap + 32 * ks);
;                   const bf16x8 Br = *(const LAS bf16x8*)(wrp + 32 * ks), Bi = *(const LAS bf16x8*)(wip + 32 * ks);
;                   zr = __builtin_amdgcn_mfma_f32_32x32x16_bf16(A, Br, zr, 0, 0, 0); zi = __builtin_amdgcn_mfma_f32_32x32x16_bf16(A, Bi, zi, 0, 0, 0); } }
;             unsigned xcb[16], pk[16];
; #pragma unroll
;             for (int v = 0; v < 16; ++v) { const int s = sbase + v; const int tl = dir == 0 ? s : 255 - s; xcb[v] = *(const LAS bf16_t*)(XC + tl * XC_PITCH + chl * 2);
;                 if (dir == 0) pk[v] = *(const LAS bf16_t*)(TIN + tl * IO_NP + nl * 2); else pk[v] = *(const LAS unsigned*)(TIN + tl * IO_WP + nl * 4); }
;             float Pp = 1.f, E = 0.f;
; #pragma unroll
;             for (int v = 0; v < 16; ++v) {
;                 const float xcv = __uint_as_float(xcb[v] << 16);
;                 const float r = __builtin_amdgcn_rcpf(1.0f + __builtin_amdgcn_exp2f(zr[v]));
;                 const float ig = __builtin_amdgcn_rcpf(1.0f + __builtin_amdgcn_exp2f(zi[v]));
;                 const float a = __builtin_amdgcn_exp2f(cl * r);
;                 const float sq = __builtin_amdgcn_sqrtf(fmaf(-a, a, 1.0f));
;                 const float u = sq * ig * xcv;
;                 E = fmaf(a, E, u); Pp *= a; zr[v] = E; zi[v] = Pp; }
.LBB0_311:
	ds_read_b128 v[128:131], v172
	ds_read_b128 v[48:51], v173
	ds_read_b128 v[132:135], v172 offset:32
	ds_read_b128 v[52:55], v173 offset:32
	ds_read_b128 v[224:227], v172 offset:64
	ds_read_b128 v[56:59], v173 offset:64
	ds_read_b128 v[228:231], v172 offset:96
	ds_read_b128 v[60:63], v173 offset:96
	ds_read_b128 v[232:235], v172 offset:128
	ds_read_b128 v[236:239], v172 offset:160
	ds_read_b128 v[240:243], v172 offset:192
	ds_read_b128 v[244:247], v172 offset:224
	ds_read_b128 v[248:251], v173 offset:8704
	ds_read_b128 v[146:149], v173 offset:8736
	s_waitcnt lgkmcnt(12)
	v_mfma_f32_32x32x16_bf16 v[32:47], v[128:131], v[48:51], v[0:15]
	ds_read_b128 v[48:51], v173 offset:128
	s_waitcnt lgkmcnt(11)
	v_mfma_f32_32x32x16_bf16 v[32:47], v[132:135], v[52:55], v[32:47]
	ds_read_b128 v[52:55], v173 offset:160
	s_waitcnt lgkmcnt(10)
	v_mfma_f32_32x32x16_bf16 v[32:47], v[224:227], v[56:59], v[32:47]
	ds_read_b128 v[56:59], v173 offset:192
	s_waitcnt lgkmcnt(9)
	v_mfma_f32_32x32x16_bf16 v[32:47], v[228:231], v[60:63], v[32:47]
	ds_read_b128 v[60:63], v173 offset:224
	s_waitcnt lgkmcnt(3)
	v_mfma_f32_32x32x16_bf16 v[32:47], v[232:235], v[48:51], v[32:47]
	s_waitcnt lgkmcnt(2)
	v_mfma_f32_32x32x16_bf16 v[32:47], v[236:239], v[52:55], v[32:47]
	s_waitcnt lgkmcnt(1)
	v_mfma_f32_32x32x16_bf16 v[32:47], v[240:243], v[56:59], v[32:47]
	s_waitcnt lgkmcnt(0)
	v_mfma_f32_32x32x16_bf16 v[32:47], v[244:247], v[60:63], v[32:47]
	v_mfma_f32_32x32x16_bf16 v[48:63], v[128:131], v[248:251], v[16:31]
	ds_read_b128 v[128:131], v173 offset:8768
	s_nop 9
	v_exp_f32_e32 v32, v32
	v_exp_f32_e32 v33, v33
	v_exp_f32_e32 v34, v34
	v_exp_f32_e32 v35, v35
	v_exp_f32_e32 v36, v36
	v_exp_f32_e32 v37, v37
	v_exp_f32_e32 v38, v38
	v_exp_f32_e32 v39, v39
	v_mfma_f32_32x32x16_bf16 v[48:63], v[132:135], v[146:149], v[48:63]
	ds_read_b128 v[132:135], v173 offset:8800
	v_exp_f32_e32 v40, v40
	v_exp_f32_e32 v41, v41
	v_exp_f32_e32 v42, v42
	v_exp_f32_e32 v43, v43
	v_exp_f32_e32 v44, v44
	v_exp_f32_e32 v45, v45
	v_exp_f32_e32 v46, v46
	v_exp_f32_e32 v47, v47
	s_waitcnt lgkmcnt(1)
	v_mfma_f32_32x32x16_bf16 v[48:63], v[224:227], v[128:131], v[48:63]
	ds_read_b128 v[224:227], v173 offset:8832
	v_fma_f32 v32, v32, v159, v159
	v_fma_f32 v33, v33, v159, v159
	v_fma_f32 v34, v34, v159, v159
	v_fma_f32 v35, v35, v159, v159
	v_fma_f32 v36, v36, v159, v159
	v_fma_f32 v37, v37, v159, v159
	v_fma_f32 v38, v38, v159, v159
	v_fma_f32 v39, v39, v159, v159
	s_waitcnt lgkmcnt(1)
	v_mfma_f32_32x32x16_bf16 v[48:63], v[228:231], v[132:135], v[48:63]
	ds_read_b128 v[228:231], v173 offset:8864
	v_fma_f32 v40, v40, v159, v159
	v_fma_f32 v41, v41, v159, v159
	v_fma_f32 v42, v42, v159, v159
	v_fma_f32 v43, v43, v159, v159
	v_fma_f32 v44, v44, v159, v159
	v_fma_f32 v45, v45, v159, v159
	v_fma_f32 v46, v46, v159, v159
	v_fma_f32 v47, v47, v159, v159
	s_waitcnt lgkmcnt(1)
	v_mfma_f32_32x32x16_bf16 v[48:63], v[232:235], v[224:227], v[48:63]
	ds_read_b128 v[128:131], v173 offset:8896
	v_rcp_f32_e32 v32, v32
	v_rcp_f32_e32 v33, v33
	v_rcp_f32_e32 v34, v34
	v_rcp_f32_e32 v35, v35
	v_rcp_f32_e32 v36, v36
	v_rcp_f32_e32 v37, v37
	v_rcp_f32_e32 v38, v38
	v_rcp_f32_e32 v39, v39
	s_waitcnt lgkmcnt(1)
	v_mfma_f32_32x32x16_bf16 v[48:63], v[236:239], v[228:231], v[48:63]
	ds_read_b128 v[132:135], v173 offset:8928
	v_rcp_f32_e32 v40, v40
	v_rcp_f32_e32 v41, v41
	v_rcp_f32_e32 v42, v42
	v_rcp_f32_e32 v43, v43
	v_rcp_f32_e32 v44, v44
	v_rcp_f32_e32 v45, v45
	v_rcp_f32_e32 v46, v46
	v_rcp_f32_e32 v47, v47
	s_waitcnt lgkmcnt(1)
	v_mfma_f32_32x32x16_bf16 v[48:63], v[240:243], v[128:131], v[48:63]
	v_exp_f32_e32 v32, v32
	v_exp_f32_e32 v33, v33
	v_exp_f32_e32 v34, v34
	v_exp_f32_e32 v35, v35
	v_exp_f32_e32 v36, v36
	v_exp_f32_e32 v37, v37
	v_exp_f32_e32 v38, v38
	v_exp_f32_e32 v39, v39
	s_waitcnt lgkmcnt(0)
	v_mfma_f32_32x32x16_bf16 v[48:63], v[244:247], v[132:135], v[48:63]
	v_exp_f32_e32 v40, v40
	v_exp_f32_e32 v41, v41
	v_exp_f32_e32 v42, v42
	v_exp_f32_e32 v43, v43
	v_exp_f32_e32 v44, v44
	v_exp_f32_e32 v45, v45
	v_exp_f32_e32 v46, v46
	v_exp_f32_e32 v47, v47
	ds_read_u16 v162, v174
	ds_read_b32 v226, v175
	ds_read_u16 v163, v176
	ds_read_b32 v225, v177
	ds_read_u16 v232, v178
	ds_read_b32 v224, v179
	ds_read_u16 v233, v180
	ds_read_b32 v223, v181
	ds_read_u16 v234, v182
	ds_read_b32 v135, v183
	ds_read_u16 v235, v184
	ds_read_b32 v134, v185
	ds_read_u16 v236, v186
	ds_read_b32 v133, v187
	ds_read_u16 v237, v188
	ds_read_b32 v131, v189
	ds_read_u16 v146, v190
	ds_read_b32 v132, v191
	ds_read_u16 v147, v192
	ds_read_b32 v130, v193
	ds_read_u16 v148, v194
	ds_read_b32 v129, v195
	ds_read_u16 v149, v196
	ds_read_b32 v128, v197
	ds_read_u16 v239, v198
	ds_read_b32 v67, v199
	ds_read_u16 v240, v200
	ds_read_b32 v66, v201
	ds_read_u16 v241, v202
	ds_read_b32 v64, v203
	ds_read_u16 v242, v204
	ds_read_b32 v251, v205
	v_exp_f32_e32 v48, v48
	v_exp_f32_e32 v49, v49
	v_exp_f32_e32 v50, v50
	v_exp_f32_e32 v51, v51
	v_exp_f32_e32 v52, v52
	v_exp_f32_e32 v53, v53
	v_exp_f32_e32 v54, v54
	v_exp_f32_e32 v55, v55
	v_exp_f32_e32 v56, v56
	v_exp_f32_e32 v57, v57
	v_exp_f32_e32 v58, v58
	v_exp_f32_e32 v59, v59
	v_exp_f32_e32 v60, v60
	v_exp_f32_e32 v61, v61
	v_exp_f32_e32 v62, v62
	v_exp_f32_e32 v63, v63
	v_add_f32_e32 v48, 1.0, v48
	v_add_f32_e32 v49, 1.0, v49
	v_add_f32_e32 v50, 1.0, v50
	v_add_f32_e32 v51, 1.0, v51
	v_add_f32_e32 v52, 1.0, v52
	v_add_f32_e32 v53, 1.0, v53
	v_add_f32_e32 v54, 1.0, v54
	v_add_f32_e32 v55, 1.0, v55
	v_add_f32_e32 v56, 1.0, v56
	v_add_f32_e32 v57, 1.0, v57
	v_add_f32_e32 v58, 1.0, v58
	v_add_f32_e32 v59, 1.0, v59
	v_add_f32_e32 v60, 1.0, v60
	v_add_f32_e32 v61, 1.0, v61
	v_add_f32_e32 v62, 1.0, v62
	v_add_f32_e32 v63, 1.0, v63
	s_waitcnt lgkmcnt(0)
; template <int dir>
; __device__ __forceinline__ void lru_pass(LAS unsigned char* lds, const Params& P, int b, int h, int q, bool dry) {
;     ...
;             for (int v = 0; v < 16; ++v) {
;                 const float xcv = __uint_as_float(xcb[v] << 16);
;                 const float r = __builtin_amdgcn_rcpf(1.0f + __builtin_amdgcn_exp2f(zr[v]));
;                 const float ig = __builtin_amdgcn_rcpf(1.0f + __builtin_amdgcn_exp2f(zi[v]));
;                 const float a = __builtin_amdgcn_exp2f(cl * r);
;                 const float sq = __builtin_amdgcn_sqrtf(fmaf(-a, a, 1.0f));
;                 const float u = sq * ig * xcv;
;                 E = fmaf(a, E, u); Pp *= a; zr[v] = E; zi[v] = Pp; }
;             const float Po = __shfl_xor(Pp, 32), Eo = __shfl_xor(E, 32);
;             const float P0 = g ? Po : Pp, E0 = g ? Eo : E, P1 = g ? Pp : Po, E1 = g ? E : Eo;
;             if (g == 0) { AGG[(wid * 2 + 0) * 32 + nl] = P0 * P1; AGG[(wid * 2 + 1) * 32 + nl] = fmaf(P1, E0, E1); }
	v_fma_f32 v244, -v32, v32, 1.0
	v_fma_f32 v245, -v33, v33, 1.0
	v_fma_f32 v246, -v34, v34, 1.0
	v_fma_f32 v247, -v35, v35, 1.0
	v_mul_f32_e32 v48, v48, v48
	v_mul_f32_e32 v49, v49, v49
	v_mul_f32_e32 v50, v50, v50
	v_mul_f32_e32 v51, v51, v51
	v_mul_f32_e32 v48, v48, v244
	v_mul_f32_e32 v49, v49, v245
	v_mul_f32_e32 v50, v50, v246
	v_mul_f32_e32 v51, v51, v247
	v_max_f32_e32 v48, 0x0da24260, v48
	v_max_f32_e32 v49, 0x0da24260, v49
	v_max_f32_e32 v50, 0x0da24260, v50
	v_max_f32_e32 v51, 0x0da24260, v51
	v_rsq_f32_e32 v48, v48
	v_rsq_f32_e32 v49, v49
	v_rsq_f32_e32 v50, v50
	v_rsq_f32_e32 v51, v51
	v_lshlrev_b32_e32 v162, 16, v162
	v_lshlrev_b32_e32 v163, 16, v163
	v_lshlrev_b32_e32 v232, 16, v232
	v_lshlrev_b32_e32 v233, 16, v233
	v_mul_f32_e32 v244, v244, v48
	v_mul_f32_e32 v245, v245, v49
	v_mul_f32_e32 v246, v246, v50
	v_mul_f32_e32 v247, v247, v51
	v_mul_f32_e32 v49, v244, v162
	v_mul_f32_e32 v228, v245, v163
	v_mul_f32_e32 v229, v246, v232
	v_mul_f32_e32 v230, v247, v233
	v_fma_f32 v244, -v36, v36, 1.0
	v_fma_f32 v245, -v37, v37, 1.0
	v_fma_f32 v246, -v38, v38, 1.0
	v_fma_f32 v247, -v39, v39, 1.0
	v_mul_f32_e32 v52, v52, v52
	v_mul_f32_e32 v53, v53, v53
	v_mul_f32_e32 v54, v54, v54
	v_mul_f32_e32 v55, v55, v55
	v_mul_f32_e32 v52, v52, v244
	v_mul_f32_e32 v53, v53, v245
	v_mul_f32_e32 v54, v54, v246
	v_mul_f32_e32 v55, v55, v247
	v_max_f32_e32 v52, 0x0da24260, v52
	v_max_f32_e32 v53, 0x0da24260, v53
	v_max_f32_e32 v54, 0x0da24260, v54
	v_max_f32_e32 v55, 0x0da24260, v55
	v_rsq_f32_e32 v52, v52
	v_rsq_f32_e32 v53, v53
	v_rsq_f32_e32 v54, v54
	v_rsq_f32_e32 v55, v55
	v_lshlrev_b32_e32 v234, 16, v234
	v_lshlrev_b32_e32 v235, 16, v235
	v_lshlrev_b32_e32 v236, 16, v236
	v_lshlrev_b32_e32 v237, 16, v237
	v_mul_f32_e32 v244, v244, v52
	v_mul_f32_e32 v245, v245, v53
	v_mul_f32_e32 v246, v246, v54
	v_mul_f32_e32 v247, v247, v55
	v_mul_f32_e32 v231, v244, v234
	v_mul_f32_e32 v232, v245, v235
	v_mul_f32_e32 v233, v246, v236
	v_mul_f32_e32 v234, v247, v237
	v_fma_f32 v244, -v40, v40, 1.0
	v_fma_f32 v245, -v41, v41, 1.0
	v_fma_f32 v246, -v42, v42, 1.0
	v_fma_f32 v247, -v43, v43, 1.0
	v_mul_f32_e32 v56, v56, v56
	v_mul_f32_e32 v57, v57, v57
	v_mul_f32_e32 v58, v58, v58
	v_mul_f32_e32 v59, v59, v59
	v_mul_f32_e32 v56, v56, v244
	v_mul_f32_e32 v57, v57, v245
	v_mul_f32_e32 v58, v58, v246
	v_mul_f32_e32 v59, v59, v247
	v_max_f32_e32 v56, 0x0da24260, v56
	v_max_f32_e32 v57, 0x0da24260, v57
	v_max_f32_e32 v58, 0x0da24260, v58
	v_max_f32_e32 v59, 0x0da24260, v59
	v_rsq_f32_e32 v56, v56
	v_rsq_f32_e32 v57, v57
	v_rsq_f32_e32 v58, v58
	v_rsq_f32_e32 v59, v59
	v_lshlrev_b32_e32 v146, 16, v146
	v_lshlrev_b32_e32 v147, 16, v147
	v_lshlrev_b32_e32 v148, 16, v148
	v_lshlrev_b32_e32 v149, 16, v149
	v_mul_f32_e32 v244, v244, v56
	v_mul_f32_e32 v245, v245, v57
	v_mul_f32_e32 v246, v246, v58
	v_mul_f32_e32 v247, v247, v59
	v_mul_f32_e32 v235, v244, v146
	v_mul_f32_e32 v236, v245, v147
	v_mul_f32_e32 v237, v246, v148
	v_mul_f32_e32 v238, v247, v149
	v_fma_f32 v244, -v44, v44, 1.0
	v_fma_f32 v245, -v45, v45, 1.0
	v_fma_f32 v246, -v46, v46, 1.0
	v_fma_f32 v247, -v47, v47, 1.0
	v_mul_f32_e32 v60, v60, v60
	v_mul_f32_e32 v61, v61, v61
	v_mul_f32_e32 v62, v62, v62
	v_mul_f32_e32 v63, v63, v63
	v_mul_f32_e32 v60, v60, v244
	v_mul_f32_e32 v61, v61, v245
	v_mul_f32_e32 v62, v62, v246
	v_mul_f32_e32 v63, v63, v247
	v_max_f32_e32 v60, 0x0da24260, v60
	v_max_f32_e32 v61, 0x0da24260, v61
	v_max_f32_e32 v62, 0x0da24260, v62
	v_max_f32_e32 v63, 0x0da24260, v63
	v_rsq_f32_e32 v60, v60
	v_rsq_f32_e32 v61, v61
	v_rsq_f32_e32 v62, v62
	v_rsq_f32_e32 v63, v63
	v_lshlrev_b32_e32 v239, 16, v239
	v_lshlrev_b32_e32 v240, 16, v240
	v_lshlrev_b32_e32 v241, 16, v241
	v_lshlrev_b32_e32 v242, 16, v242
	v_mul_f32_e32 v244, v244, v60
	v_mul_f32_e32 v245, v245, v61
	v_mul_f32_e32 v246, v246, v62
	v_mul_f32_e32 v247, v247, v63
	v_mul_f32_e32 v239, v244, v239
	v_mul_f32_e32 v240, v245, v240
	v_mul_f32_e32 v63, v246, v241
	v_mul_f32_e32 v241, v247, v242
	v_mov_b32_e32 v227, v32
	v_fmac_f32_e32 v49, 0, v32
	v_fmac_f32_e32 v228, v33, v49
	v_mul_f32_e32 v50, v227, v33
	v_fmac_f32_e32 v229, v34, v228
	v_mul_f32_e32 v51, v50, v34
	v_fmac_f32_e32 v230, v35, v229
	v_mul_f32_e32 v52, v51, v35
	v_fmac_f32_e32 v231, v36, v230
	v_mul_f32_e32 v53, v52, v36
	v_fmac_f32_e32 v232, v37, v231
	v_mul_f32_e32 v54, v53, v37
	v_fmac_f32_e32 v233, v38, v232
	v_mul_f32_e32 v55, v54, v38
	v_fmac_f32_e32 v234, v39, v233
	v_mul_f32_e32 v56, v55, v39
	v_fmac_f32_e32 v235, v40, v234
	v_mul_f32_e32 v57, v56, v40
	v_fmac_f32_e32 v236, v41, v235
	v_mul_f32_e32 v58, v57, v41
	v_fmac_f32_e32 v237, v42, v236
	v_mul_f32_e32 v59, v58, v42
	v_fmac_f32_e32 v238, v43, v237
	v_mul_f32_e32 v60, v59, v43
	v_fmac_f32_e32 v239, v44, v238
	v_mul_f32_e32 v61, v60, v44
	v_fmac_f32_e32 v240, v45, v239
	v_mul_f32_e32 v62, v61, v45
	v_fmac_f32_e32 v63, v46, v240
	v_mul_f32_e32 v243, v62, v46
	v_fmac_f32_e32 v241, v47, v63
	v_mul_f32_e32 v242, v243, v47
	v_mov_b32_e32 v244, v242
	v_mov_b32_e32 v246, v242
	v_mov_b32_e32 v245, v241
	v_mov_b32_e32 v247, v241
	s_nop 1
	v_permlane32_swap_b32 v244, v246
	v_permlane32_swap_b32 v245, v247
	s_and_saveexec_b64 s[18:19], vcc
	s_cbranch_execz .LBB0_313
	v_fma_f32 v32, v246, v245, v247
	v_mul_f32_e32 v33, v244, v246
	v_add_u32_e32 v35, s98, v254
	ds_write2_b32 v35, v33, v32 offset1:32
